# static s_setprio 1 for waves 4-7 during the attention phase (reset at phase exit)
# baseline (speedup 1.0000x reference)
; #define LAS __attribute__((address_space(3)))
; __device__ __forceinline__ void phase_attention(bf16_t* __restrict__ qh, const bf16_t* __restrict__ kh, const bf16_t* __restrict__ vb, float* __restrict__ lse, LAS unsigned char* obuf, const int nseq, const int S) {
;   const int tid = otid(), lane = tid & 63, rl = lane & 31, h = lane >> 5;
;   const int nw = gridDim.x * 8, wv = tid >> 6;
;   const int nitem = 48 * (TS / 32), per = (nitem + nw - 1) / nw;
;   const int bbase = obid() * per * 8;
;   const int ipq = S / 32;
;   const int kap = (rl & ~12) | ((rl & 4) << 1) | ((rl & 8) >> 1);
;   const float SC = 0.08838834764831845f * LOG2E;
; #pragma nounroll
;   for (int it = 0; it < per; ++it) {
;     const int item = bbase + it * 8 + wv;
;     if (item >= nitem) break;
;     const int hs = item / ipq, rem = item % ipq;
;     const int hh = hs / nseq, seq = hs % nseq;
;     const int g = hh >> 4, lg = 2 * g, dil = 1 << lg, L = S >> lg, nqb = L >> 5;
;     const int r = rem / nqb, qb = rem % nqb, m0 = qb * 32;
;     const float sl2 = exp2f(-8.f * (float)(hh + 1) / 48.f) * (float)dil * LOG2E;
;     const size_t pbase = (size_t)seq * S + (size_t)r * L;
;     bf16_t* qrow = qh + ((size_t)hh * TS + pbase + m0 + rl) * 128;
;     bf16x8 qf[8];
;     { LAS unsigned char* qb_ = obuf + wv * 10240;
;       const bf16_t* qt = qrow - (size_t)rl * 128 + (size_t)lane * 8;
;       u32x4 qraw[8];
; #pragma unroll
;       for (int i = 0; i < 8; ++i) qraw[i] = *(const u32x4*)(qt + i * 512);
; #pragma unroll
;       for (int i = 0; i < 8; ++i) *(LAS u32x4*)(qb_ + (lane >> 4) * 272 + (lane & 15) * 16 + i * (4 * 272)) = qraw[i];
; #pragma unroll
;       for (int kk = 0; kk < 8; ++kk) qf[kk] = *(const LAS bf16x8*)(qb_ + rl * 272 + 16 * h + 32 * kk); }
;     const bf16_t* kt0 = kh + ((size_t)hh * TS + pbase) * 128 + (size_t)lane * 8;
;     const bf16_t* vt0 = vb + ((size_t)hh * (TS / 32) + (pbase >> 5)) * 4096 + (size_t)lane * 8;
;     LAS unsigned char* tb = obuf + wv * 10240;
;     const int kw = ((lane >> 4)) * 272 + (lane & 15) * 16, kr = kap * 272 + 16 * h;
;     const int vw = (lane >> 2) * 80 + (lane & 3) * 16, vr = rl * 80 + 16 * h;
;     f32x16 o[4];
; #pragma unroll
;     for (int db = 0; db < 4; ++db)
; #pragma unroll
;       for (int e = 0; e < 16; ++e) o[db][e] = 0.f;
;     float mrun = -1e30f, lrun = 0.f;
.LBB0_709:
	s_or_b64 exec, exec, s[2:3]
	v_mov_b64_e32 v[0:1], s[10:11]
	s_waitcnt lgkmcnt(0)
	s_barrier
	s_nop 0
	v_readfirstlane_b32 s100, v252
	s_nop 3
	s_cmpk_lt_u32 s100, 0x100
	s_cbranch_scc1 .Lattn_noprio
	s_setprio 1
.Lattn_noprio:
	global_load_dwordx2 v[2:3], v[0:1], off sc0 sc1
	s_waitcnt vmcnt(0)
	global_load_dwordx2 v[4:5], v[0:1], off sc0 sc1
	s_waitcnt vmcnt(0)
	global_load_dwordx2 v[6:7], v[0:1], off sc0 sc1
	s_waitcnt vmcnt(0)
	global_load_dwordx2 v[8:9], v[0:1], off sc0 sc1
	s_waitcnt vmcnt(0)
	v_mov_b32_e32 v0, v252
	v_mov_b32_e32 v1, s74
	ds_read_b32 v1, v1
	v_readlane_b32 s0, v255, 11
	v_readlane_b32 s1, v255, 12
	s_andn2_b64 vcc, exec, s[0:1]
	s_waitcnt lgkmcnt(0)
	v_readfirstlane_b32 s0, v1
	v_readfirstlane_b32 s5, v3
	v_readfirstlane_b32 s4, v2
	v_readfirstlane_b32 s3, v5
	v_readfirstlane_b32 s2, v4
	v_readfirstlane_b32 s9, v7
	v_readfirstlane_b32 s8, v6
	v_readfirstlane_b32 s1, v9
	v_readfirstlane_b32 s13, v8
	s_cbranch_vccnz .LBB0_723
	s_add_u32 s8, s8, 0x30180000
	s_addc_u32 s9, s9, 0
	s_add_u32 s36, s13, 0x40180000
	s_addc_u32 s37, s1, 0
	v_readlane_b32 s1, v255, 10
	s_mul_i32 s0, s0, s1
	s_lshr_b32 s1, s17, 5
	v_cvt_f32_u32_e32 v12, s1
	v_cvt_f32_ubyte0_e32 v18, s89
	v_lshlrev_b32_e32 v2, 1, v0
	v_lshrrev_b32_e32 v3, 1, v0
	v_rcp_iflag_f32_e32 v17, v12
	v_rcp_iflag_f32_e32 v18, v18
	v_ashrrev_i32_e32 v237, 6, v0
	v_and_b32_e32 v1, 19, v0
	v_and_b32_e32 v2, 8, v2
	v_and_b32_e32 v3, 4, v3
	s_movk_i32 s13, 0x2800
	v_or3_b32 v1, v1, v2, v3
	v_and_b32_e32 v184, 31, v0
	v_mul_lo_u32 v2, v237, s13
	v_mul_f32_e32 v17, 0x4f7ffffe, v17
	v_add_u32_e32 v6, 0, v2
	v_mul_hi_i32_i24_e32 v3, 0xffffff00, v184
	v_mul_i32_i24_e32 v2, 0xffffff00, v184
	v_cvt_u32_f32_e32 v17, v17
	v_lshl_add_u64 v[2:3], s[4:5], 0, v[2:3]
	s_mov_b64 s[4:5], 0x18180000
	v_mul_f32_e32 v18, 0x4f7ffffe, v18
	v_and_b32_e32 v4, 63, v0
	v_lshl_add_u64 v[186:187], v[2:3], 0, s[4:5]
	v_bfe_u32 v7, v0, 4, 2
	s_movk_i32 s4, 0x110
	v_cvt_u32_f32_e32 v18, v18
	v_mad_u32_u24 v238, v7, s4, v6
	v_mad_u32_u24 v239, v184, s4, v6
	v_lshlrev_b32_e32 v80, 4, v4
	v_mad_u32_u24 v1, v1, s4, v6
	s_sub_i32 s4, 0, s1
	v_lshl_add_u64 v[2:3], s[2:3], 0, v[80:81]
	s_mov_b64 s[2:3], 0x24180000
	v_mul_lo_u32 v19, s4, v17
	v_bfe_u32 v5, v0, 5, 1
	v_lshlrev_b32_e32 v8, 4, v0
	v_lshl_add_u64 v[190:191], v[2:3], 0, s[2:3]
	v_and_b32_e32 v2, 15, v0
	v_bfe_u32 v0, v0, 2, 4
	s_movk_i32 s2, 0x50
	v_mul_hi_u32 v19, v17, v19
	s_sub_i32 s4, 0, s89
	v_lshlrev_b32_e32 v188, 3, v4
	v_lshlrev_b32_e32 v241, 4, v2
	v_mad_u32_u24 v13, v0, s2, v6
	v_mad_u32_u24 v15, v184, s2, v6
	v_lshlrev_b32_e32 v0, 3, v2
	v_cmp_gt_u32_e64 s[2:3], 32, v4
	v_lshlrev_b32_e32 v2, 7, v7
	v_or_b32_e32 v4, 4, v7
	v_add_u32_e32 v243, v17, v19
	v_mul_lo_u32 v17, s4, v18
	v_mul_u32_u24_e32 v9, 0x110, v7
	v_and_b32_e32 v11, 0xf0, v8
	v_lshlrev_b32_e32 v240, 4, v5
	v_and_b32_e32 v3, 48, v8
	v_lshlrev_b32_e32 v242, 3, v5
	v_add_u32_e32 v5, v6, v241
	v_mul_u32_u24_e32 v7, 0x110, v4
	v_lshlrev_b32_e32 v4, 7, v4
	v_or_b32_e32 v6, 0x400, v2
	v_or_b32_e32 v8, 0x600, v2
	v_or_b32_e32 v10, 0x800, v2
	v_or_b32_e32 v12, 0xa00, v2
	v_or_b32_e32 v14, 0xc00, v2
	v_or_b32_e32 v16, 0xe00, v2
	v_mul_hi_u32 v17, v18, v17
	s_mov_b32 s13, 0
	v_add_u32_e32 v244, v18, v17
	v_sub_u32_e32 v245, v242, v184
	s_mov_b64 s[40:41], 0
	v_add_u32_e32 v246, v238, v11
	v_add_u32_e32 v247, v1, v240
	v_add_u32_e32 v248, v13, v3
	v_add_u32_e32 v249, v15, v240
	v_lshlrev_b32_e32 v192, 1, v0
	v_add_u32_e32 v250, v5, v9
	v_lshlrev_b32_e32 v194, 1, v2
	v_add_u32_e32 v251, v5, v7
	v_lshlrev_b32_e32 v196, 1, v4
	v_lshlrev_b32_e32 v198, 1, v6
	v_lshlrev_b32_e32 v200, 1, v8
	v_lshlrev_b32_e32 v202, 1, v10
	v_lshlrev_b32_e32 v204, 1, v12
	v_lshlrev_b32_e32 v206, 1, v14
	v_lshlrev_b32_e32 v208, 1, v16
	s_branch .LBB0_713

; #define LAS __attribute__((address_space(3)))
; __device__ __forceinline__ int otid() { int t = threadIdx.x; asm volatile("" : "+v"(t)); return t; }
; __device__ __forceinline__ unsigned xb_add(unsigned* p, unsigned v) { return __hip_atomic_fetch_add(p, v, __ATOMIC_RELAXED, __HIP_MEMORY_SCOPE_AGENT); }
; __device__ __forceinline__ void gbar(unsigned* bar, unsigned n, volatile LAS unsigned* st) {
;   asm volatile("s_waitcnt vmcnt(0)" ::: "memory");
;   __syncthreads();
;   if (otid() == 0) {
;     __builtin_amdgcn_s_waitcnt(0);
;     const unsigned x = st[0], nloc = st[1], nx = st[2];
;     const unsigned old = xb_add(&bar[XB_XSUB(x)], 1u);
;     unsigned sp = 0;
;     if (old + 1u == (n + 1u) * nloc) {
;       __builtin_amdgcn_fence(__ATOMIC_RELEASE, "agent");
;       asm volatile("s_waitcnt vmcnt(0)" ::: "memory");
;       xb_add(&bar[XB_TOP], 1u);
.LBB0_723:
	s_setprio 0
	v_mov_b64_e32 v[0:1], s[10:11]
	global_load_dwordx2 v[0:1], v[0:1], off sc0 sc1
	s_waitcnt vmcnt(0)
	s_waitcnt vmcnt(0)
	v_mov_b32_e32 v2, v252
	s_waitcnt lgkmcnt(0)
	s_barrier
	v_add_u32_e32 v4, 3, v236
	v_cmp_ne_u32_e32 vcc, 0, v2
	v_readfirstlane_b32 s0, v1
	v_readfirstlane_b32 s1, v0
	s_and_saveexec_b64 s[2:3], vcc
	s_xor_b64 s[2:3], exec, s[2:3]
	v_add_u32_e32 v4, 3, v236
	s_andn2_saveexec_b64 s[2:3], s[2:3]
	s_cbranch_execz .LBB0_773
	v_readlane_b32 s8, v255, 15
	s_waitcnt vmcnt(0) expcnt(0) lgkmcnt(0)
	s_add_u32 s4, s1, 0x4cc80000
	v_mov_b32_e32 v0, s8
	ds_read_b32 v1, v0
	v_readlane_b32 s8, v255, 16
	s_addc_u32 s5, s0, 0
	s_waitcnt lgkmcnt(0)
	v_lshlrev_b32_e32 v1, 6, v1
	v_add_u32_e32 v80, 0x440, v1
	v_mov_b32_e32 v0, s8
	v_readlane_b32 s8, v255, 17
	v_lshlrev_b64 v[2:3], 2, v[80:81]
	ds_read_b32 v5, v0
	v_mov_b32_e32 v0, s8
	v_lshl_add_u64 v[2:3], s[4:5], 0, v[2:3]
	ds_read_b32 v0, v0
	global_atomic_add v2, v[2:3], v230, off sc0
	s_waitcnt lgkmcnt(0)
	v_mul_lo_u32 v3, v5, v4
	v_add_u32_e32 v80, 0x840, v1
	s_waitcnt vmcnt(0)
	v_add_u32_e32 v2, 1, v2
	v_cmp_ne_u32_e32 vcc, v2, v3
	s_and_saveexec_b64 s[8:9], vcc
	s_xor_b64 s[8:9], exec, s[8:9]
	s_cbranch_execz .LBB0_749
	v_lshlrev_b64 v[0:1], 2, v[80:81]
	v_lshl_add_u64 v[0:1], s[4:5], 0, v[0:1]
	s_mov_b32 s13, 0x1000000
	s_mov_b64 s[36:37], 0
	s_branch .LBB0_737
